# speedup vs baseline: 1.0749x; 1.0012x over previous
; __device__ __forceinline__ int tid_opaque() { int t = threadIdx.x; asm volatile("" : "+v"(t)); return t; }
; __device__ __forceinline__ void phase_E(const Params& p, int l) {
;     const bf16_t* P1 = (const bf16_t*)(p.ws + WS_P1);
;     const float* PART = (const float*)(p.ws + WS_PART);
;     const float* xin = (l == 0) ? p.x : p.out;
;     const float* gpost = p.norm_post + l * 1024;
;     const int etid = tid_opaque(); const int lane = etid & 63, wv = etid >> 6;
;     const int nextra = (l == 0) ? NWT_IN : 0;
;     constexpr int RPW = 4;
;     constexpr int NIT = M_ / (8 * RPW);
;     for (int it = blockIdx.x; it < NIT + nextra; it += gridDim.x) {
;         if (it >= NIT) { convert_weights_tile(p, 1, it - NIT); continue; }
;         const int rowb = it * 8 * RPW + wv * RPW;
;         float ps[RPW]; uint2 ov[RPW][4]; float4 xv[RPW][4];
; #pragma unroll
;         for (int r = 0; r < RPW; ++r) {
;             const int row = rowb + r;
;             ps[r] = (lane < 16) ? PART[(long)row * 16 + lane] : 0.f;
; #pragma unroll
;             for (int i = 0; i < 4; ++i) {
;                 const int c = lane * 4 + 256 * i;
;                 ov[r][i] = ld_nt_u2(P1 + (long)row * P1W + 2560 + c);
;                 xv[r][i] = ld_nt_f4(xin + (long)row * 1024 + c);
;             }
;         }
;         float4 gg[4];
; #pragma unroll
;         for (int i = 0; i < 4; ++i) gg[i] = *reinterpret_cast<const float4*>(gpost + lane * 4 + 256 * i);
.LBB0_512:
	s_or_b64 exec, exec, s[0:1]
	v_readlane_b32 s4, v234, 47
	v_readlane_b32 s5, v234, 48
	s_and_b64 s[0:1], s[4:5], exec
	s_movk_i32 s0, 0x200
	s_cselect_b32 s2, s0, 0x200
	s_mov_b64 s[0:1], s[4:5]
	v_mov_b32_e32 v0, v208
	s_cmp_ge_i32 s50, s2
	s_waitcnt lgkmcnt(0)
	s_barrier
	s_cbranch_scc1 .LBB0_542
	v_readlane_b32 s4, v234, 28
	s_and_b64 s[0:1], s[0:1], exec
	v_readlane_b32 s5, v234, 29
	s_mov_b64 s[0:1], s[4:5]
	v_readlane_b32 s3, v234, 46
	s_cselect_b32 s1, s1, s45
	s_cselect_b32 s0, s0, s44
	s_lshl_b32 s72, s3, 10
	s_lshl_b64 s[4:5], s[72:73], 2
	v_and_b32_e32 v2, 63, v0
	s_add_u32 s4, s42, s4
	s_addc_u32 s5, s43, s5
	v_lshlrev_b32_e32 v80, 2, v2
	v_lshlrev_b32_e32 v128, 4, v2
	v_ashrrev_i32_e32 v0, 4, v0
	v_lshl_add_u64 v[84:85], s[4:5], 0, v[128:129]
	v_or_b32_e32 v86, 0x100, v80
	v_readlane_b32 s4, v234, 26
	v_and_b32_e32 v3, -4, v0
	v_or_b32_e32 v88, 0x200, v80
	v_readlane_b32 s5, v234, 27
	v_lshlrev_b32_e32 v0, 2, v86
	v_mov_b32_e32 v1, v129
	v_or_b32_e32 v90, 0x300, v80
	v_lshl_add_u64 v[94:95], s[4:5], 0, v[0:1]
	v_lshlrev_b32_e32 v0, 2, v88
	v_readlane_b32 s6, v234, 30
	v_readlane_b32 s7, v234, 31
	v_mov_b32_e32 v81, v129
	v_lshl_add_u64 v[92:93], s[4:5], 0, v[128:129]
	v_lshl_add_u64 v[96:97], s[4:5], 0, v[0:1]
	v_lshlrev_b32_e32 v0, 2, v90
	v_lshl_add_u64 v[100:101], s[0:1], 0, v[128:129]
	v_lshlrev_b32_e32 v128, 3, v2
	s_and_b32 s98, s50, 7
	s_lshl_b32 s98, s98, 11
	s_lshr_b32 s99, s50, 3
	s_and_b32 s99, s99, 7
	s_lshl_b32 s99, s99, 8
	s_add_i32 s98, s98, s99
	s_lshr_b32 s99, s50, 6
	s_lshl_b32 s99, s99, 6
	s_add_i32 s0, s98, s99
	v_cmp_gt_u32_e64 s[6:7], 16, v2
	v_lshl_add_u64 v[82:83], s[96:97], 0, v[80:81]
	v_lshl_add_u64 v[98:99], s[4:5], 0, v[0:1]
	v_lshl_add_u64 v[102:103], s[74:75], 0, v[128:129]
	v_add_u32_e32 v104, s0, v3
	global_load_dwordx4 v[164:167], v[92:93], off
	global_load_dwordx4 v[168:171], v[94:95], off
	global_load_dwordx4 v[172:175], v[96:97], off
	global_load_dwordx4 v[176:179], v[98:99], off
	s_mov_b32 s3, s50
	v_readlane_b32 s8, v234, 32
	v_readlane_b32 s9, v234, 33
	v_readlane_b32 s10, v234, 34
	v_readlane_b32 s11, v234, 35
	s_branch .LBB0_517

; __device__ __forceinline__ void phase_E(const Params& p, int l) {
;     ...
;         for (int r = 0; r < RPW; ++r) {
;             const int row = rowb + r;
;             ps[r] = (lane < 16) ? PART[(long)row * 16 + lane] : 0.f;
; #pragma unroll
;             for (int i = 0; i < 4; ++i) {
;                 const int c = lane * 4 + 256 * i;
;                 ov[r][i] = ld_nt_u2(P1 + (long)row * P1W + 2560 + c);
;                 xv[r][i] = ld_nt_f4(xin + (long)row * 1024 + c);
;             }
;         }
;         float4 gg[4];
; #pragma unroll
;         for (int i = 0; i < 4; ++i) gg[i] = *reinterpret_cast<const float4*>(gpost + lane * 4 + 256 * i);
; #pragma unroll
;         for (int r = 0; r < RPW; ++r) {
;             const int row = rowb + r;
;             const float inv = rsqrtf(wave_sum(ps[r]) * (1.0f / 1024.f) + 1e-6f);
;             float ss = 0.f;
; #pragma unroll
;             for (int i = 0; i < 4; ++i) {
;                 const int c = lane * 4 + 256 * i;
;                 float4 xn;
;                 xn.x = xv[r][i].x + bflo(ov[r][i].x) * inv * gg[i].x; xn.y = xv[r][i].y + bfhi(ov[r][i].x) * inv * gg[i].y;
;                 xn.z = xv[r][i].z + bflo(ov[r][i].y) * inv * gg[i].z; xn.w = xv[r][i].w + bfhi(ov[r][i].y) * inv * gg[i].w;
;                 ss += xn.x * xn.x + xn.y * xn.y + xn.z * xn.z + xn.w * xn.w;
;                 st16_wt(p.out + (long)row * 1024 + c, make_uint4(__builtin_bit_cast(unsigned, xn.x), __builtin_bit_cast(unsigned, xn.y), __builtin_bit_cast(unsigned, xn.z), __builtin_bit_cast(unsigned, xn.w)));
.LBB0_526:
	s_or_b64 exec, exec, s[0:1]
	v_lshlrev_b64 v[6:7], 13, v[106:107]
	v_lshl_add_u64 v[6:7], s[46:47], 0, v[6:7]
	s_mov_b64 s[0:1], 0x3431400
	v_lshl_add_u64 v[6:7], v[6:7], 0, s[0:1]
	v_lshlrev_b64 v[114:115], 12, v[106:107]
	v_lshl_add_u64 v[8:9], v[6:7], 0, v[128:129]
	v_lshl_add_u64 v[16:17], v[100:101], 0, v[114:115]
	v_lshl_add_u64 v[0:1], v[6:7], 0, v[0:1]
	global_load_dwordx2 v[116:117], v[8:9], off nt
	global_load_dwordx4 v[20:23], v[16:17], off nt
	global_load_dwordx2 v[112:113], v[0:1], off nt
	global_load_dwordx4 v[12:15], v[16:17], off offset:1024 nt
	v_lshl_add_u64 v[0:1], v[6:7], 0, v[2:3]
	global_load_dwordx2 v[110:111], v[0:1], off nt
	global_load_dwordx4 v[8:11], v[16:17], off offset:2048 nt
	v_lshl_add_u64 v[0:1], v[6:7], 0, v[4:5]
	global_load_dwordx2 v[108:109], v[0:1], off nt
	s_nop 0
	global_load_dwordx4 v[0:3], v[16:17], off offset:3072 nt
	global_load_dwordx4 v[28:31], v[84:85], off
	global_load_dwordx4 v[24:27], v[84:85], off offset:1024
	s_nop 0
	global_load_dwordx4 v[16:19], v[84:85], off offset:2048
	global_load_dwordx4 v[4:7], v[84:85], off offset:3072
	v_and_b32_e32 v81, 64, v213
	v_add_u32_e32 v128, 64, v81
	v_xor_b32_e32 v81, 32, v213
	v_cmp_lt_i32_e32 vcc, v81, v128
	v_xor_b32_e32 v87, 16, v213
	v_xor_b32_e32 v89, 8, v213
	v_cndmask_b32_e32 v81, v213, v81, vcc
	v_cmp_lt_i32_e32 vcc, v87, v128
	v_xor_b32_e32 v91, 4, v213
	v_xor_b32_e32 v154, 2, v213
	v_cndmask_b32_e32 v87, v213, v87, vcc
	v_cmp_lt_i32_e32 vcc, v89, v128
	v_xor_b32_e32 v155, 1, v213
	v_lshlrev_b32_e32 v81, 2, v81
	v_cndmask_b32_e32 v89, v213, v89, vcc
	v_cmp_lt_i32_e32 vcc, v91, v128
	v_lshlrev_b32_e32 v87, 2, v87
	v_lshlrev_b32_e32 v89, 2, v89
	v_cndmask_b32_e32 v91, v213, v91, vcc
	v_cmp_lt_i32_e32 vcc, v154, v128
	v_lshlrev_b32_e32 v91, 2, v91
	s_waitcnt vmcnt(0)
	v_lshlrev_b32_e32 v162, 16, v152
	v_cndmask_b32_e32 v154, v213, v154, vcc
	v_cmp_lt_i32_e32 vcc, v155, v128
	v_lshlrev_b32_e32 v154, 2, v154
	v_and_b32_e32 v163, 0xffff0000, v152
	v_cndmask_b32_e32 v128, v213, v155, vcc
	v_lshlrev_b32_e32 v155, 2, v128
	ds_bpermute_b32 v128, v81, v159
	v_lshlrev_b32_e32 v152, 16, v153
	v_and_b32_e32 v153, 0xffff0000, v153
	v_lshl_add_u64 v[150:151], s[44:45], 0, v[150:151]
	s_mov_b64 s[0:1], 0x800
	s_waitcnt lgkmcnt(0)
	v_add_f32_e32 v128, v159, v128
	ds_bpermute_b32 v159, v87, v128
	s_waitcnt lgkmcnt(0)
	v_add_f32_e32 v128, v128, v159
	s_nop 1
	v_mov_b32_dpp v159, v128 row_ror:8 row_mask:0xf bank_mask:0xf
	s_waitcnt lgkmcnt(0)
	v_add_f32_e32 v128, v128, v159
	s_nop 1
	v_mov_b32_dpp v159, v128 row_ror:4 row_mask:0xf bank_mask:0xf
	s_waitcnt lgkmcnt(0)
	v_add_f32_e32 v128, v128, v159
	s_nop 1
	v_mov_b32_dpp v159, v128 row_ror:2 row_mask:0xf bank_mask:0xf
	s_waitcnt lgkmcnt(0)
	v_add_f32_e32 v128, v128, v159
	s_nop 1
	v_mov_b32_dpp v159, v128 row_ror:1 row_mask:0xf bank_mask:0xf
	s_waitcnt lgkmcnt(0)
	v_add_f32_e32 v128, v128, v159
	v_fmamk_f32 v128, v128, 0x3a800000, v211
	v_cmp_gt_f32_e32 vcc, s94, v128
	v_mul_f32_e32 v159, 0x4b800000, v128
	s_nop 0
	v_cndmask_b32_e32 v128, v128, v159, vcc
	v_rsq_f32_e32 v128, v128
	s_nop 0
	v_mul_f32_e32 v159, 0x45800000, v128
	v_cndmask_b32_e32 v160, v128, v159, vcc
	v_pk_mul_f32 v[152:153], v[160:161], v[152:153] op_sel_hi:[0,1]
	v_pk_fma_f32 v[78:79], v[30:31], v[152:153], v[78:79]
	v_lshlrev_b32_e32 v128, 2, v80
	v_lshlrev_b32_e32 v152, 16, v148
	v_and_b32_e32 v153, 0xffff0000, v148
	v_lshlrev_b32_e32 v148, 16, v149
	v_and_b32_e32 v149, 0xffff0000, v149
	v_pk_mul_f32 v[162:163], v[160:161], v[162:163] op_sel_hi:[0,1]
	v_lshl_add_u64 v[150:151], v[150:151], 0, v[128:129]
	v_pk_mul_f32 v[148:149], v[160:161], v[148:149] op_sel_hi:[0,1]
	v_pk_fma_f32 v[76:77], v[28:29], v[162:163], v[76:77]
	v_pk_mul_f32 v[152:153], v[160:161], v[152:153] op_sel_hi:[0,1]
	global_store_dwordx4 v[150:151], v[76:79], off sc1
	s_nop 1
	v_pk_fma_f32 v[74:75], v[26:27], v[148:149], v[74:75]
	v_lshl_add_u64 v[148:149], v[150:151], 0, s[48:49]
	v_pk_fma_f32 v[72:73], v[24:25], v[152:153], v[72:73]
	s_nop 0
	global_store_dwordx4 v[148:149], v[72:75], off sc1
	s_nop 1
	v_lshlrev_b32_e32 v148, 16, v146
	v_and_b32_e32 v149, 0xffff0000, v146
	v_lshlrev_b32_e32 v146, 16, v147
	v_and_b32_e32 v147, 0xffff0000, v147
	v_pk_mul_f32 v[146:147], v[160:161], v[146:147] op_sel_hi:[0,1]
	v_pk_mul_f32 v[148:149], v[160:161], v[148:149] op_sel_hi:[0,1]
	v_pk_fma_f32 v[70:71], v[18:19], v[146:147], v[70:71]
	v_lshl_add_u64 v[146:147], v[150:151], 0, s[0:1]
	v_pk_fma_f32 v[68:69], v[16:17], v[148:149], v[68:69]
	s_mov_b64 s[0:1], 0xc00
	global_store_dwordx4 v[146:147], v[68:71], off sc1
	s_nop 1
	v_lshlrev_b32_e32 v146, 16, v144
	v_and_b32_e32 v147, 0xffff0000, v144
	v_lshlrev_b32_e32 v144, 16, v145
	v_and_b32_e32 v145, 0xffff0000, v145
	v_pk_mul_f32 v[144:145], v[160:161], v[144:145] op_sel_hi:[0,1]
	v_pk_mul_f32 v[146:147], v[160:161], v[146:147] op_sel_hi:[0,1]
	v_pk_fma_f32 v[66:67], v[6:7], v[144:145], v[66:67]
	v_lshl_add_u64 v[144:145], v[150:151], 0, s[0:1]
	v_readlane_b32 s0, v234, 47
	v_pk_fma_f32 v[64:65], v[4:5], v[146:147], v[64:65]
	v_readlane_b32 s1, v234, 48
	global_store_dwordx4 v[144:145], v[64:67], off sc1
	s_nop 1
	s_andn2_b64 vcc, exec, s[0:1]
	s_nop 0
	v_cndmask_b32_e64 v144, 0, 1, s[0:1]
	v_cmp_ne_u32_e64 s[4:5], 1, v144
	s_cbranch_vccnz .LBB0_528
; __device__ __forceinline__ void phase_E(const Params& p, int l) {
;     ...
;         for (int r = 0; r < RPW; ++r) {
;             const int row = rowb + r;
;             const float inv = rsqrtf(wave_sum(ps[r]) * (1.0f / 1024.f) + 1e-6f);
;             float ss = 0.f;
; #pragma unroll
;             for (int i = 0; i < 4; ++i) {
;                 const int c = lane * 4 + 256 * i;
;                 float4 xn;
;                 xn.x = xv[r][i].x + bflo(ov[r][i].x) * inv * gg[i].x; xn.y = xv[r][i].y + bfhi(ov[r][i].x) * inv * gg[i].y;
;                 xn.z = xv[r][i].z + bflo(ov[r][i].y) * inv * gg[i].z; xn.w = xv[r][i].w + bfhi(ov[r][i].y) * inv * gg[i].w;
;                 ss += xn.x * xn.x + xn.y * xn.y + xn.z * xn.z + xn.w * xn.w;
;                 st16_wt(p.out + (long)row * 1024 + c, make_uint4(__builtin_bit_cast(unsigned, xn.x), __builtin_bit_cast(unsigned, xn.y), __builtin_bit_cast(unsigned, xn.z), __builtin_bit_cast(unsigned, xn.w)));
;     ...
;             if (l == 0) {
;                 ss = wave_sum(ss);
;                 const float inv2 = rsqrtf(ss * (1.0f / 1024.f) + 1e-6f);
;                 bf16_t* hr = (bf16_t*)(p.ws + WS_H) + (long)row * 1024;
;                 const float* g2 = p.norm_pre + 1024;
; #pragma unroll
;                 for (int i = 0; i < 4; ++i) {
;                     const int c = lane * 4 + 256 * i;
;                     float4 g4 = *reinterpret_cast<const float4*>(g2 + c);
;                     uint2 o; o.x = pk2(xv[r][i].x * inv2 * g4.x, xv[r][i].y * inv2 * g4.y); o.y = pk2(xv[r][i].z * inv2 * g4.z, xv[r][i].w * inv2 * g4.w);
;                     *reinterpret_cast<uint2*>(hr + c) = o;
;                 }
	v_mov_b32_e32 v148, v77
	v_mov_b32_e32 v149, v73
	v_mov_b32_e32 v146, v76
	v_mov_b32_e32 v147, v72
	v_pk_mul_f32 v[148:149], v[148:149], v[148:149]
	v_mov_b32_e32 v150, v65
	v_pk_fma_f32 v[146:147], v[146:147], v[146:147], v[148:149]
	v_mov_b32_e32 v148, v78
	v_mov_b32_e32 v149, v74
	v_mov_b32_e32 v151, v69
	v_pk_fma_f32 v[146:147], v[148:149], v[148:149], v[146:147]
	v_mov_b32_e32 v148, v64
	v_mov_b32_e32 v149, v68
	v_pk_mul_f32 v[150:151], v[150:151], v[150:151]
	v_mov_b32_e32 v144, v79
	v_mov_b32_e32 v145, v75
	v_pk_fma_f32 v[148:149], v[148:149], v[148:149], v[150:151]
	v_mov_b32_e32 v150, v66
	v_mov_b32_e32 v151, v70
	v_pk_fma_f32 v[144:145], v[144:145], v[144:145], v[146:147]
	v_mov_b32_e32 v146, v67
	v_mov_b32_e32 v147, v71
	v_pk_fma_f32 v[148:149], v[150:151], v[150:151], v[148:149]
	v_add_f32_e32 v144, v144, v145
	v_pk_fma_f32 v[146:147], v[146:147], v[146:147], v[148:149]
	v_mov_b32_e32 v148, v164
	v_mov_b32_e32 v149, v165
	v_mov_b32_e32 v150, v166
	v_mov_b32_e32 v151, v167
	v_add_f32_e32 v144, v147, v144
	v_add_f32_e32 v144, v146, v144
	ds_bpermute_b32 v145, v81, v144
	v_lshlrev_b64 v[146:147], 11, v[104:105]
	v_lshl_add_u64 v[146:147], v[102:103], 0, v[146:147]
	s_waitcnt lgkmcnt(0)
	v_add_f32_e32 v144, v144, v145
	ds_bpermute_b32 v145, v87, v144
	s_waitcnt lgkmcnt(0)
	v_add_f32_e32 v144, v144, v145
	s_nop 1
	v_mov_b32_dpp v145, v144 row_ror:8 row_mask:0xf bank_mask:0xf
	s_waitcnt lgkmcnt(0)
	v_add_f32_e32 v144, v144, v145
	s_nop 1
	v_mov_b32_dpp v145, v144 row_ror:4 row_mask:0xf bank_mask:0xf
	s_waitcnt lgkmcnt(0)
	v_add_f32_e32 v144, v144, v145
	s_nop 1
	v_mov_b32_dpp v145, v144 row_ror:2 row_mask:0xf bank_mask:0xf
	s_waitcnt lgkmcnt(0)
	v_add_f32_e32 v144, v144, v145
	s_nop 1
	v_mov_b32_dpp v145, v144 row_ror:1 row_mask:0xf bank_mask:0xf
	s_waitcnt lgkmcnt(0)
	v_add_f32_e32 v144, v144, v145
	v_fmamk_f32 v144, v144, 0x3a800000, v211
	v_cmp_gt_f32_e32 vcc, s94, v144
	v_mul_f32_e32 v145, 0x4b800000, v144
	s_nop 0
	v_cndmask_b32_e32 v144, v144, v145, vcc
	v_rsq_f32_e32 v144, v144
	s_nop 0
	v_mul_f32_e32 v145, 0x45800000, v144
	v_cndmask_b32_e32 v144, v144, v145, vcc
	v_pk_mul_f32 v[76:77], v[76:77], v[144:145] op_sel_hi:[1,0]
	v_pk_mul_f32 v[78:79], v[78:79], v[144:145] op_sel_hi:[1,0]
	v_pk_mul_f32 v[72:73], v[72:73], v[144:145] op_sel_hi:[1,0]
	v_pk_mul_f32 v[74:75], v[74:75], v[144:145] op_sel_hi:[1,0]
	v_pk_mul_f32 v[68:69], v[68:69], v[144:145] op_sel_hi:[1,0]
	v_pk_mul_f32 v[70:71], v[70:71], v[144:145] op_sel_hi:[1,0]
	v_pk_mul_f32 v[64:65], v[64:65], v[144:145] op_sel_hi:[1,0]
	v_pk_mul_f32 v[66:67], v[66:67], v[144:145] op_sel_hi:[1,0]
	s_nop 0
	v_pk_mul_f32 v[76:77], v[148:149], v[76:77]
	v_pk_mul_f32 v[78:79], v[150:151], v[78:79]
	v_cvt_pk_bf16_f32 v76, v76, v77
	v_cvt_pk_bf16_f32 v77, v78, v79
	global_store_dwordx2 v[146:147], v[76:77], off
	v_mov_b32_e32 v76, v168
	v_mov_b32_e32 v77, v169
	v_mov_b32_e32 v78, v170
	v_mov_b32_e32 v79, v171
	s_nop 0
	v_pk_mul_f32 v[72:73], v[76:77], v[72:73]
	v_pk_mul_f32 v[74:75], v[74:75], v[78:79]
	v_cvt_pk_bf16_f32 v72, v72, v73
	v_cvt_pk_bf16_f32 v73, v74, v75
	global_store_dwordx2 v[146:147], v[72:73], off offset:512
	v_mov_b32_e32 v72, v172
	v_mov_b32_e32 v73, v173
	v_mov_b32_e32 v74, v174
	v_mov_b32_e32 v75, v175
	s_nop 0
	v_pk_mul_f32 v[68:69], v[68:69], v[72:73]
	v_pk_mul_f32 v[70:71], v[70:71], v[74:75]
	v_cvt_pk_bf16_f32 v68, v68, v69
	v_cvt_pk_bf16_f32 v69, v70, v71
	global_store_dwordx2 v[146:147], v[68:69], off offset:1024
	v_mov_b32_e32 v68, v176
	v_mov_b32_e32 v69, v177
	v_mov_b32_e32 v70, v178
	v_mov_b32_e32 v71, v179
	s_nop 0
	v_pk_mul_f32 v[64:65], v[64:65], v[68:69]
	v_pk_mul_f32 v[66:67], v[66:67], v[70:71]
	v_cvt_pk_bf16_f32 v64, v64, v65
	v_cvt_pk_bf16_f32 v65, v66, v67
	global_store_dwordx2 v[146:147], v[64:65], off offset:1536
.LBB0_528:
	ds_bpermute_b32 v64, v81, v158
	v_lshlrev_b32_e32 v66, 16, v142
	v_and_b32_e32 v67, 0xffff0000, v142
	v_lshlrev_b32_e32 v68, 16, v138
	v_and_b32_e32 v69, 0xffff0000, v138
	s_waitcnt lgkmcnt(0)
	v_add_f32_e32 v64, v158, v64
	ds_bpermute_b32 v65, v87, v64
	s_mov_b64 s[0:1], 0x800
	s_waitcnt lgkmcnt(0)
	v_add_f32_e32 v64, v64, v65
	s_nop 1
	v_mov_b32_dpp v65, v64 row_ror:8 row_mask:0xf bank_mask:0xf
	s_waitcnt lgkmcnt(0)
	v_add_f32_e32 v64, v64, v65
	s_nop 1
	v_mov_b32_dpp v65, v64 row_ror:4 row_mask:0xf bank_mask:0xf
	s_waitcnt lgkmcnt(0)
	v_add_f32_e32 v64, v64, v65
	s_nop 1
	v_mov_b32_dpp v65, v64 row_ror:2 row_mask:0xf bank_mask:0xf
	s_waitcnt lgkmcnt(0)
	v_add_f32_e32 v64, v64, v65
	s_nop 1
	v_mov_b32_dpp v65, v64 row_ror:1 row_mask:0xf bank_mask:0xf
	s_waitcnt lgkmcnt(0)
	v_add_f32_e32 v64, v64, v65
	v_fmamk_f32 v64, v64, 0x3a800000, v211
	v_cmp_gt_f32_e32 vcc, s94, v64
	v_mul_f32_e32 v65, 0x4b800000, v64
	s_nop 0
	v_cndmask_b32_e32 v64, v64, v65, vcc
	v_rsq_f32_e32 v64, v64
	s_nop 0
	v_mul_f32_e32 v65, 0x45800000, v64
	v_cndmask_b32_e32 v64, v64, v65, vcc
	v_pk_mul_f32 v[66:67], v[64:65], v[66:67] op_sel_hi:[0,1]
	v_pk_fma_f32 v[60:61], v[28:29], v[66:67], v[60:61]
	v_lshlrev_b32_e32 v66, 16, v143
	v_and_b32_e32 v67, 0xffff0000, v143
	v_pk_mul_f32 v[66:67], v[64:65], v[66:67] op_sel_hi:[0,1]
	v_pk_mul_f32 v[68:69], v[64:65], v[68:69] op_sel_hi:[0,1]
	v_pk_fma_f32 v[62:63], v[30:31], v[66:67], v[62:63]
	v_lshl_add_u64 v[66:67], s[44:45], 0, v[140:141]
	v_pk_fma_f32 v[56:57], v[24:25], v[68:69], v[56:57]
	v_lshlrev_b32_e32 v68, 16, v139
	v_and_b32_e32 v69, 0xffff0000, v139
	v_lshl_add_u64 v[66:67], v[66:67], 0, v[128:129]
	v_pk_mul_f32 v[68:69], v[64:65], v[68:69] op_sel_hi:[0,1]
	global_store_dwordx4 v[66:67], v[60:63], off sc1
	s_nop 1
	v_pk_fma_f32 v[58:59], v[26:27], v[68:69], v[58:59]
	v_lshl_add_u64 v[68:69], v[66:67], 0, s[48:49]
	global_store_dwordx4 v[68:69], v[56:59], off sc1
	s_nop 1
	v_lshlrev_b32_e32 v68, 16, v136
	v_and_b32_e32 v69, 0xffff0000, v136
	v_pk_mul_f32 v[68:69], v[64:65], v[68:69] op_sel_hi:[0,1]
	v_pk_fma_f32 v[52:53], v[16:17], v[68:69], v[52:53]
	v_lshlrev_b32_e32 v68, 16, v137
	v_and_b32_e32 v69, 0xffff0000, v137
	v_pk_mul_f32 v[68:69], v[64:65], v[68:69] op_sel_hi:[0,1]
	v_pk_fma_f32 v[54:55], v[18:19], v[68:69], v[54:55]
	v_lshl_add_u64 v[68:69], v[66:67], 0, s[0:1]
	global_store_dwordx4 v[68:69], v[52:55], off sc1
	s_nop 1
	v_lshlrev_b32_e32 v68, 16, v134
	v_and_b32_e32 v69, 0xffff0000, v134
	v_pk_mul_f32 v[68:69], v[64:65], v[68:69] op_sel_hi:[0,1]
	v_pk_fma_f32 v[48:49], v[4:5], v[68:69], v[48:49]
	v_lshlrev_b32_e32 v68, 16, v135
	v_and_b32_e32 v69, 0xffff0000, v135
	v_pk_mul_f32 v[64:65], v[64:65], v[68:69] op_sel_hi:[0,1]
	s_mov_b64 s[0:1], 0xc00
	v_pk_fma_f32 v[50:51], v[6:7], v[64:65], v[50:51]
	v_lshl_add_u64 v[64:65], v[66:67], 0, s[0:1]
	global_store_dwordx4 v[64:65], v[48:51], off sc1
	s_nop 1
	s_and_b64 vcc, exec, s[4:5]
	s_cbranch_vccnz .LBB0_530
; __device__ __forceinline__ void phase_E(const Params& p, int l) {
;     ...
;         for (int r = 0; r < RPW; ++r) {
;             const int row = rowb + r;
;             const float inv = rsqrtf(wave_sum(ps[r]) * (1.0f / 1024.f) + 1e-6f);
;             float ss = 0.f;
; #pragma unroll
;             for (int i = 0; i < 4; ++i) {
;                 const int c = lane * 4 + 256 * i;
;                 float4 xn;
;                 xn.x = xv[r][i].x + bflo(ov[r][i].x) * inv * gg[i].x; xn.y = xv[r][i].y + bfhi(ov[r][i].x) * inv * gg[i].y;
;                 xn.z = xv[r][i].z + bflo(ov[r][i].y) * inv * gg[i].z; xn.w = xv[r][i].w + bfhi(ov[r][i].y) * inv * gg[i].w;
;                 ss += xn.x * xn.x + xn.y * xn.y + xn.z * xn.z + xn.w * xn.w;
;                 st16_wt(p.out + (long)row * 1024 + c, make_uint4(__builtin_bit_cast(unsigned, xn.x), __builtin_bit_cast(unsigned, xn.y), __builtin_bit_cast(unsigned, xn.z), __builtin_bit_cast(unsigned, xn.w)));
;     ...
;             if (l == 0) {
;                 ss = wave_sum(ss);
;                 const float inv2 = rsqrtf(ss * (1.0f / 1024.f) + 1e-6f);
;                 bf16_t* hr = (bf16_t*)(p.ws + WS_H) + (long)row * 1024;
;                 const float* g2 = p.norm_pre + 1024;
; #pragma unroll
;                 for (int i = 0; i < 4; ++i) {
;                     const int c = lane * 4 + 256 * i;
;                     float4 g4 = *reinterpret_cast<const float4*>(g2 + c);
;                     uint2 o; o.x = pk2(xv[r][i].x * inv2 * g4.x, xv[r][i].y * inv2 * g4.y); o.y = pk2(xv[r][i].z * inv2 * g4.z, xv[r][i].w * inv2 * g4.w);
;                     *reinterpret_cast<uint2*>(hr + c) = o;
;                 }
	v_mov_b32_e32 v68, v61
	v_mov_b32_e32 v69, v57
	v_mov_b32_e32 v66, v60
	v_mov_b32_e32 v67, v56
	v_pk_mul_f32 v[68:69], v[68:69], v[68:69]
	v_mov_b32_e32 v70, v49
	v_pk_fma_f32 v[66:67], v[66:67], v[66:67], v[68:69]
	v_mov_b32_e32 v68, v62
	v_mov_b32_e32 v69, v58
	v_mov_b32_e32 v71, v53
	v_pk_fma_f32 v[66:67], v[68:69], v[68:69], v[66:67]
	v_mov_b32_e32 v68, v48
	v_mov_b32_e32 v69, v52
	v_pk_mul_f32 v[70:71], v[70:71], v[70:71]
	v_mov_b32_e32 v64, v63
	v_mov_b32_e32 v65, v59
	v_pk_fma_f32 v[68:69], v[68:69], v[68:69], v[70:71]
	v_mov_b32_e32 v70, v50
	v_mov_b32_e32 v71, v54
	v_pk_fma_f32 v[64:65], v[64:65], v[64:65], v[66:67]
	v_mov_b32_e32 v66, v51
	v_mov_b32_e32 v67, v55
	v_pk_fma_f32 v[68:69], v[70:71], v[70:71], v[68:69]
	v_add_f32_e32 v64, v64, v65
	v_pk_fma_f32 v[66:67], v[66:67], v[66:67], v[68:69]
	v_mov_b32_e32 v68, v164
	v_mov_b32_e32 v69, v165
	v_mov_b32_e32 v70, v166
	v_mov_b32_e32 v71, v167
	v_add_f32_e32 v64, v67, v64
	v_add_f32_e32 v64, v66, v64
	ds_bpermute_b32 v65, v81, v64
	v_lshlrev_b64 v[66:67], 11, v[132:133]
	v_lshl_add_u64 v[66:67], v[102:103], 0, v[66:67]
	s_waitcnt lgkmcnt(0)
	v_add_f32_e32 v64, v64, v65
	ds_bpermute_b32 v65, v87, v64
	s_waitcnt lgkmcnt(0)
	v_add_f32_e32 v64, v64, v65
	s_nop 1
	v_mov_b32_dpp v65, v64 row_ror:8 row_mask:0xf bank_mask:0xf
	s_waitcnt lgkmcnt(0)
	v_add_f32_e32 v64, v64, v65
	s_nop 1
	v_mov_b32_dpp v65, v64 row_ror:4 row_mask:0xf bank_mask:0xf
	s_waitcnt lgkmcnt(0)
	v_add_f32_e32 v64, v64, v65
	s_nop 1
	v_mov_b32_dpp v65, v64 row_ror:2 row_mask:0xf bank_mask:0xf
	s_waitcnt lgkmcnt(0)
	v_add_f32_e32 v64, v64, v65
	s_nop 1
	v_mov_b32_dpp v65, v64 row_ror:1 row_mask:0xf bank_mask:0xf
	s_waitcnt lgkmcnt(0)
	v_add_f32_e32 v64, v64, v65
	v_fmamk_f32 v64, v64, 0x3a800000, v211
	v_cmp_gt_f32_e32 vcc, s94, v64
	v_mul_f32_e32 v65, 0x4b800000, v64
	s_nop 0
	v_cndmask_b32_e32 v64, v64, v65, vcc
	v_rsq_f32_e32 v64, v64
	s_nop 0
	v_mul_f32_e32 v65, 0x45800000, v64
	v_cndmask_b32_e32 v64, v64, v65, vcc
	v_pk_mul_f32 v[60:61], v[60:61], v[64:65] op_sel_hi:[1,0]
	v_pk_mul_f32 v[62:63], v[62:63], v[64:65] op_sel_hi:[1,0]
	v_pk_mul_f32 v[56:57], v[56:57], v[64:65] op_sel_hi:[1,0]
	v_pk_mul_f32 v[58:59], v[58:59], v[64:65] op_sel_hi:[1,0]
	v_pk_mul_f32 v[52:53], v[52:53], v[64:65] op_sel_hi:[1,0]
	v_pk_mul_f32 v[54:55], v[54:55], v[64:65] op_sel_hi:[1,0]
	v_pk_mul_f32 v[48:49], v[48:49], v[64:65] op_sel_hi:[1,0]
	v_pk_mul_f32 v[50:51], v[50:51], v[64:65] op_sel_hi:[1,0]
	s_nop 0
	v_pk_mul_f32 v[60:61], v[68:69], v[60:61]
	v_pk_mul_f32 v[62:63], v[70:71], v[62:63]
	v_cvt_pk_bf16_f32 v60, v60, v61
	v_cvt_pk_bf16_f32 v61, v62, v63
	global_store_dwordx2 v[66:67], v[60:61], off
	v_mov_b32_e32 v60, v168
	v_mov_b32_e32 v61, v169
	v_mov_b32_e32 v62, v170
	v_mov_b32_e32 v63, v171
	s_nop 0
	v_pk_mul_f32 v[56:57], v[60:61], v[56:57]
	v_pk_mul_f32 v[58:59], v[58:59], v[62:63]
	v_cvt_pk_bf16_f32 v56, v56, v57
	v_cvt_pk_bf16_f32 v57, v58, v59
	global_store_dwordx2 v[66:67], v[56:57], off offset:512
	v_mov_b32_e32 v56, v172
	v_mov_b32_e32 v57, v173
	v_mov_b32_e32 v58, v174
	v_mov_b32_e32 v59, v175
	s_nop 0
	v_pk_mul_f32 v[52:53], v[52:53], v[56:57]
	v_pk_mul_f32 v[54:55], v[54:55], v[58:59]
	v_cvt_pk_bf16_f32 v52, v52, v53
	v_cvt_pk_bf16_f32 v53, v54, v55
	global_store_dwordx2 v[66:67], v[52:53], off offset:1024
	v_mov_b32_e32 v52, v176
	v_mov_b32_e32 v53, v177
	v_mov_b32_e32 v54, v178
	v_mov_b32_e32 v55, v179
	s_nop 0
	v_pk_mul_f32 v[48:49], v[48:49], v[52:53]
	v_pk_mul_f32 v[50:51], v[50:51], v[54:55]
	v_cvt_pk_bf16_f32 v48, v48, v49
	v_cvt_pk_bf16_f32 v49, v50, v51
	global_store_dwordx2 v[66:67], v[48:49], off offset:1536
.LBB0_530:
	ds_bpermute_b32 v48, v81, v157
	v_lshlrev_b32_e32 v50, 16, v130
	v_and_b32_e32 v51, 0xffff0000, v130
	v_lshlrev_b32_e32 v52, 16, v124
	v_and_b32_e32 v53, 0xffff0000, v124
	s_waitcnt lgkmcnt(0)
	v_add_f32_e32 v48, v157, v48
	ds_bpermute_b32 v49, v87, v48
	s_mov_b64 s[0:1], 0x800
	s_waitcnt lgkmcnt(0)
	v_add_f32_e32 v48, v48, v49
	s_nop 1
	v_mov_b32_dpp v49, v48 row_ror:8 row_mask:0xf bank_mask:0xf
	s_waitcnt lgkmcnt(0)
	v_add_f32_e32 v48, v48, v49
	s_nop 1
	v_mov_b32_dpp v49, v48 row_ror:4 row_mask:0xf bank_mask:0xf
	s_waitcnt lgkmcnt(0)
	v_add_f32_e32 v48, v48, v49
	s_nop 1
	v_mov_b32_dpp v49, v48 row_ror:2 row_mask:0xf bank_mask:0xf
	s_waitcnt lgkmcnt(0)
	v_add_f32_e32 v48, v48, v49
	s_nop 1
	v_mov_b32_dpp v49, v48 row_ror:1 row_mask:0xf bank_mask:0xf
	s_waitcnt lgkmcnt(0)
	v_add_f32_e32 v48, v48, v49
	v_fmamk_f32 v48, v48, 0x3a800000, v211
	v_cmp_gt_f32_e32 vcc, s94, v48
	v_mul_f32_e32 v49, 0x4b800000, v48
	s_nop 0
	v_cndmask_b32_e32 v48, v48, v49, vcc
	v_rsq_f32_e32 v48, v48
	s_nop 0
	v_mul_f32_e32 v49, 0x45800000, v48
	v_cndmask_b32_e32 v48, v48, v49, vcc
	v_pk_mul_f32 v[50:51], v[48:49], v[50:51] op_sel_hi:[0,1]
	v_pk_fma_f32 v[44:45], v[28:29], v[50:51], v[44:45]
	v_lshlrev_b32_e32 v50, 16, v131
	v_and_b32_e32 v51, 0xffff0000, v131
	v_pk_mul_f32 v[50:51], v[48:49], v[50:51] op_sel_hi:[0,1]
	v_pk_mul_f32 v[52:53], v[48:49], v[52:53] op_sel_hi:[0,1]
	v_pk_fma_f32 v[46:47], v[30:31], v[50:51], v[46:47]
	v_lshl_add_u64 v[50:51], s[44:45], 0, v[126:127]
	v_pk_fma_f32 v[40:41], v[24:25], v[52:53], v[40:41]
	v_lshlrev_b32_e32 v52, 16, v125
	v_and_b32_e32 v53, 0xffff0000, v125
	v_lshl_add_u64 v[50:51], v[50:51], 0, v[128:129]
	v_pk_mul_f32 v[52:53], v[48:49], v[52:53] op_sel_hi:[0,1]
	global_store_dwordx4 v[50:51], v[44:47], off sc1
	s_nop 1
	v_pk_fma_f32 v[42:43], v[26:27], v[52:53], v[42:43]
	v_lshl_add_u64 v[52:53], v[50:51], 0, s[48:49]
	global_store_dwordx4 v[52:53], v[40:43], off sc1
	s_nop 1
	v_lshlrev_b32_e32 v52, 16, v122
	v_and_b32_e32 v53, 0xffff0000, v122
	v_pk_mul_f32 v[52:53], v[48:49], v[52:53] op_sel_hi:[0,1]
	v_pk_fma_f32 v[36:37], v[16:17], v[52:53], v[36:37]
	v_lshlrev_b32_e32 v52, 16, v123
	v_and_b32_e32 v53, 0xffff0000, v123
	v_pk_mul_f32 v[52:53], v[48:49], v[52:53] op_sel_hi:[0,1]
	v_pk_fma_f32 v[38:39], v[18:19], v[52:53], v[38:39]
	v_lshl_add_u64 v[52:53], v[50:51], 0, s[0:1]
	global_store_dwordx4 v[52:53], v[36:39], off sc1
	s_nop 1
	v_lshlrev_b32_e32 v52, 16, v120
	v_and_b32_e32 v53, 0xffff0000, v120
	v_pk_mul_f32 v[52:53], v[48:49], v[52:53] op_sel_hi:[0,1]
	v_pk_fma_f32 v[32:33], v[4:5], v[52:53], v[32:33]
	v_lshlrev_b32_e32 v52, 16, v121
	v_and_b32_e32 v53, 0xffff0000, v121
	v_pk_mul_f32 v[48:49], v[48:49], v[52:53] op_sel_hi:[0,1]
	s_mov_b64 s[0:1], 0xc00
	v_pk_fma_f32 v[34:35], v[6:7], v[48:49], v[34:35]
	v_lshl_add_u64 v[48:49], v[50:51], 0, s[0:1]
	global_store_dwordx4 v[48:49], v[32:35], off sc1
	s_nop 1
	s_and_b64 vcc, exec, s[4:5]
	s_cbranch_vccnz .LBB0_532
; __device__ __forceinline__ void phase_E(const Params& p, int l) {
;     ...
;             if (l == 0) {
;                 ss = wave_sum(ss);
;                 const float inv2 = rsqrtf(ss * (1.0f / 1024.f) + 1e-6f);
;                 bf16_t* hr = (bf16_t*)(p.ws + WS_H) + (long)row * 1024;
;                 const float* g2 = p.norm_pre + 1024;
; #pragma unroll
;                 for (int i = 0; i < 4; ++i) {
;                     const int c = lane * 4 + 256 * i;
;                     float4 g4 = *reinterpret_cast<const float4*>(g2 + c);
;                     uint2 o; o.x = pk2(xv[r][i].x * inv2 * g4.x, xv[r][i].y * inv2 * g4.y); o.y = pk2(xv[r][i].z * inv2 * g4.z, xv[r][i].w * inv2 * g4.w);
;                     *reinterpret_cast<uint2*>(hr + c) = o;
;                 }
	v_mov_b32_e32 v52, v45
	v_mov_b32_e32 v53, v41
	v_mov_b32_e32 v50, v44
	v_mov_b32_e32 v51, v40
	v_pk_mul_f32 v[52:53], v[52:53], v[52:53]
	v_mov_b32_e32 v54, v33
	v_pk_fma_f32 v[50:51], v[50:51], v[50:51], v[52:53]
	v_mov_b32_e32 v52, v46
	v_mov_b32_e32 v53, v42
	v_mov_b32_e32 v55, v37
	v_pk_fma_f32 v[50:51], v[52:53], v[52:53], v[50:51]
	v_mov_b32_e32 v52, v32
	v_mov_b32_e32 v53, v36
	v_pk_mul_f32 v[54:55], v[54:55], v[54:55]
	v_mov_b32_e32 v48, v47
	v_mov_b32_e32 v49, v43
	v_pk_fma_f32 v[52:53], v[52:53], v[52:53], v[54:55]
	v_mov_b32_e32 v54, v34
	v_mov_b32_e32 v55, v38
	v_pk_fma_f32 v[48:49], v[48:49], v[48:49], v[50:51]
	v_mov_b32_e32 v50, v35
	v_mov_b32_e32 v51, v39
	v_pk_fma_f32 v[52:53], v[54:55], v[54:55], v[52:53]
	v_add_f32_e32 v48, v48, v49
	v_pk_fma_f32 v[50:51], v[50:51], v[50:51], v[52:53]
	v_mov_b32_e32 v52, v164
	v_mov_b32_e32 v53, v165
	v_mov_b32_e32 v54, v166
	v_mov_b32_e32 v55, v167
	v_add_f32_e32 v48, v51, v48
	v_add_f32_e32 v48, v50, v48
	ds_bpermute_b32 v49, v81, v48
	v_lshlrev_b64 v[50:51], 11, v[118:119]
	v_lshl_add_u64 v[50:51], v[102:103], 0, v[50:51]
	s_waitcnt lgkmcnt(0)
	v_add_f32_e32 v48, v48, v49
	ds_bpermute_b32 v49, v87, v48
	s_waitcnt lgkmcnt(0)
	v_add_f32_e32 v48, v48, v49
	s_nop 1
	v_mov_b32_dpp v49, v48 row_ror:8 row_mask:0xf bank_mask:0xf
	s_waitcnt lgkmcnt(0)
	v_add_f32_e32 v48, v48, v49
	s_nop 1
	v_mov_b32_dpp v49, v48 row_ror:4 row_mask:0xf bank_mask:0xf
	s_waitcnt lgkmcnt(0)
	v_add_f32_e32 v48, v48, v49
	s_nop 1
	v_mov_b32_dpp v49, v48 row_ror:2 row_mask:0xf bank_mask:0xf
	s_waitcnt lgkmcnt(0)
	v_add_f32_e32 v48, v48, v49
	s_nop 1
	v_mov_b32_dpp v49, v48 row_ror:1 row_mask:0xf bank_mask:0xf
	s_waitcnt lgkmcnt(0)
	v_add_f32_e32 v48, v48, v49
	v_fmamk_f32 v48, v48, 0x3a800000, v211
	v_cmp_gt_f32_e32 vcc, s94, v48
	v_mul_f32_e32 v49, 0x4b800000, v48
	s_nop 0
	v_cndmask_b32_e32 v48, v48, v49, vcc
	v_rsq_f32_e32 v48, v48
	s_nop 0
	v_mul_f32_e32 v49, 0x45800000, v48
	v_cndmask_b32_e32 v48, v48, v49, vcc
	v_pk_mul_f32 v[44:45], v[44:45], v[48:49] op_sel_hi:[1,0]
	v_pk_mul_f32 v[46:47], v[46:47], v[48:49] op_sel_hi:[1,0]
	v_pk_mul_f32 v[40:41], v[40:41], v[48:49] op_sel_hi:[1,0]
	v_pk_mul_f32 v[42:43], v[42:43], v[48:49] op_sel_hi:[1,0]
	v_pk_mul_f32 v[36:37], v[36:37], v[48:49] op_sel_hi:[1,0]
	v_pk_mul_f32 v[38:39], v[38:39], v[48:49] op_sel_hi:[1,0]
	v_pk_mul_f32 v[32:33], v[32:33], v[48:49] op_sel_hi:[1,0]
	v_pk_mul_f32 v[34:35], v[34:35], v[48:49] op_sel_hi:[1,0]
	s_nop 0
	v_pk_mul_f32 v[44:45], v[52:53], v[44:45]
	v_pk_mul_f32 v[46:47], v[54:55], v[46:47]
	v_cvt_pk_bf16_f32 v44, v44, v45
	v_cvt_pk_bf16_f32 v45, v46, v47
	global_store_dwordx2 v[50:51], v[44:45], off
	v_mov_b32_e32 v44, v168
	v_mov_b32_e32 v45, v169
	v_mov_b32_e32 v46, v170
	v_mov_b32_e32 v47, v171
	s_nop 0
	v_pk_mul_f32 v[40:41], v[44:45], v[40:41]
	v_pk_mul_f32 v[42:43], v[42:43], v[46:47]
	v_cvt_pk_bf16_f32 v40, v40, v41
	v_cvt_pk_bf16_f32 v41, v42, v43
	global_store_dwordx2 v[50:51], v[40:41], off offset:512
	v_mov_b32_e32 v40, v172
	v_mov_b32_e32 v41, v173
	v_mov_b32_e32 v42, v174
	v_mov_b32_e32 v43, v175
	s_nop 0
	v_pk_mul_f32 v[36:37], v[36:37], v[40:41]
	v_pk_mul_f32 v[38:39], v[38:39], v[42:43]
	v_cvt_pk_bf16_f32 v36, v36, v37
	v_cvt_pk_bf16_f32 v37, v38, v39
	global_store_dwordx2 v[50:51], v[36:37], off offset:1024
	v_mov_b32_e32 v36, v176
	v_mov_b32_e32 v37, v177
	v_mov_b32_e32 v38, v178
	v_mov_b32_e32 v39, v179
	s_nop 0
	v_pk_mul_f32 v[32:33], v[32:33], v[36:37]
	v_pk_mul_f32 v[34:35], v[34:35], v[38:39]
	v_cvt_pk_bf16_f32 v32, v32, v33
	v_cvt_pk_bf16_f32 v33, v34, v35
	global_store_dwordx2 v[50:51], v[32:33], off offset:1536
; __device__ __forceinline__ void phase_E(const Params& p, int l) {
;     ...
;         for (int r = 0; r < RPW; ++r) {
;             const int row = rowb + r;
;             const float inv = rsqrtf(wave_sum(ps[r]) * (1.0f / 1024.f) + 1e-6f);
;             float ss = 0.f;
; #pragma unroll
;             for (int i = 0; i < 4; ++i) {
;                 const int c = lane * 4 + 256 * i;
;                 float4 xn;
;                 xn.x = xv[r][i].x + bflo(ov[r][i].x) * inv * gg[i].x; xn.y = xv[r][i].y + bfhi(ov[r][i].x) * inv * gg[i].y;
;                 xn.z = xv[r][i].z + bflo(ov[r][i].y) * inv * gg[i].z; xn.w = xv[r][i].w + bfhi(ov[r][i].y) * inv * gg[i].w;
;                 ss += xn.x * xn.x + xn.y * xn.y + xn.z * xn.z + xn.w * xn.w;
;                 st16_wt(p.out + (long)row * 1024 + c, make_uint4(__builtin_bit_cast(unsigned, xn.x), __builtin_bit_cast(unsigned, xn.y), __builtin_bit_cast(unsigned, xn.z), __builtin_bit_cast(unsigned, xn.w)));
;                 xv[r][i] = xn;
;             }
;             if (l == 0) {
;                 ss = wave_sum(ss);
;                 const float inv2 = rsqrtf(ss * (1.0f / 1024.f) + 1e-6f);
;                 bf16_t* hr = (bf16_t*)(p.ws + WS_H) + (long)row * 1024;
;                 const float* g2 = p.norm_pre + 1024;
; #pragma unroll
;                 for (int i = 0; i < 4; ++i) {
;                     const int c = lane * 4 + 256 * i;
;                     float4 g4 = *reinterpret_cast<const float4*>(g2 + c);
;                     uint2 o; o.x = pk2(xv[r][i].x * inv2 * g4.x, xv[r][i].y * inv2 * g4.y); o.y = pk2(xv[r][i].z * inv2 * g4.z, xv[r][i].w * inv2 * g4.w);
;                     *reinterpret_cast<uint2*>(hr + c) = o;
;                 }
.LBB0_532:
	ds_bpermute_b32 v32, v81, v156
	v_lshlrev_b32_e32 v34, 16, v116
	v_and_b32_e32 v35, 0xffff0000, v116
	s_mov_b64 s[0:1], 0x800
	s_waitcnt lgkmcnt(0)
	v_add_f32_e32 v32, v156, v32
	ds_bpermute_b32 v33, v87, v32
	s_waitcnt lgkmcnt(0)
	v_add_f32_e32 v32, v32, v33
	s_nop 1
	v_mov_b32_dpp v33, v32 row_ror:8 row_mask:0xf bank_mask:0xf
	s_waitcnt lgkmcnt(0)
	v_add_f32_e32 v32, v32, v33
	s_nop 1
	v_mov_b32_dpp v33, v32 row_ror:4 row_mask:0xf bank_mask:0xf
	s_waitcnt lgkmcnt(0)
	v_add_f32_e32 v32, v32, v33
	s_nop 1
	v_mov_b32_dpp v33, v32 row_ror:2 row_mask:0xf bank_mask:0xf
	s_waitcnt lgkmcnt(0)
	v_add_f32_e32 v32, v32, v33
	s_nop 1
	v_mov_b32_dpp v33, v32 row_ror:1 row_mask:0xf bank_mask:0xf
	s_waitcnt lgkmcnt(0)
	v_add_f32_e32 v32, v32, v33
	v_fmamk_f32 v32, v32, 0x3a800000, v211
	v_cmp_gt_f32_e32 vcc, s94, v32
	v_mul_f32_e32 v33, 0x4b800000, v32
	s_nop 0
	v_cndmask_b32_e32 v32, v32, v33, vcc
	v_rsq_f32_e32 v32, v32
	s_nop 0
	v_mul_f32_e32 v33, 0x45800000, v32
	v_cndmask_b32_e32 v32, v32, v33, vcc
	v_pk_mul_f32 v[34:35], v[32:33], v[34:35] op_sel_hi:[0,1]
	v_pk_fma_f32 v[20:21], v[28:29], v[34:35], v[20:21]
	v_lshlrev_b32_e32 v28, 16, v117
	v_and_b32_e32 v29, 0xffff0000, v117
	v_pk_mul_f32 v[28:29], v[32:33], v[28:29] op_sel_hi:[0,1]
	v_pk_fma_f32 v[22:23], v[30:31], v[28:29], v[22:23]
	v_lshlrev_b32_e32 v30, 16, v112
	v_and_b32_e32 v31, 0xffff0000, v112
	v_pk_mul_f32 v[30:31], v[32:33], v[30:31] op_sel_hi:[0,1]
	v_lshl_add_u64 v[28:29], s[44:45], 0, v[114:115]
	v_pk_fma_f32 v[12:13], v[24:25], v[30:31], v[12:13]
	v_lshlrev_b32_e32 v24, 16, v113
	v_and_b32_e32 v25, 0xffff0000, v113
	v_lshl_add_u64 v[28:29], v[28:29], 0, v[128:129]
	v_pk_mul_f32 v[24:25], v[32:33], v[24:25] op_sel_hi:[0,1]
	global_store_dwordx4 v[28:29], v[20:23], off sc1
	s_nop 1
	v_pk_fma_f32 v[14:15], v[26:27], v[24:25], v[14:15]
	v_lshl_add_u64 v[24:25], v[28:29], 0, s[48:49]
	global_store_dwordx4 v[24:25], v[12:15], off sc1
	s_nop 1
	v_lshlrev_b32_e32 v24, 16, v110
	v_and_b32_e32 v25, 0xffff0000, v110
	v_pk_mul_f32 v[24:25], v[32:33], v[24:25] op_sel_hi:[0,1]
	v_pk_fma_f32 v[8:9], v[16:17], v[24:25], v[8:9]
	v_lshlrev_b32_e32 v16, 16, v111
	v_and_b32_e32 v17, 0xffff0000, v111
	v_pk_mul_f32 v[16:17], v[32:33], v[16:17] op_sel_hi:[0,1]
	v_pk_fma_f32 v[10:11], v[18:19], v[16:17], v[10:11]
	v_lshl_add_u64 v[16:17], v[28:29], 0, s[0:1]
	global_store_dwordx4 v[16:17], v[8:11], off sc1
	s_nop 1
	v_lshlrev_b32_e32 v16, 16, v108
	v_and_b32_e32 v17, 0xffff0000, v108
	v_pk_mul_f32 v[16:17], v[32:33], v[16:17] op_sel_hi:[0,1]
	v_pk_fma_f32 v[0:1], v[4:5], v[16:17], v[0:1]
	v_lshlrev_b32_e32 v4, 16, v109
	v_and_b32_e32 v5, 0xffff0000, v109
	v_pk_mul_f32 v[4:5], v[32:33], v[4:5] op_sel_hi:[0,1]
	s_mov_b64 s[0:1], 0xc00
	v_pk_fma_f32 v[2:3], v[6:7], v[4:5], v[2:3]
	v_lshl_add_u64 v[4:5], v[28:29], 0, s[0:1]
	global_store_dwordx4 v[4:5], v[0:3], off sc1
	s_nop 1
	s_and_b64 vcc, exec, s[4:5]
	s_cbranch_vccnz .LBB0_534
	v_mov_b32_e32 v16, v21
	v_mov_b32_e32 v17, v13
	v_mov_b32_e32 v6, v20
	v_mov_b32_e32 v7, v12
	v_pk_mul_f32 v[16:17], v[16:17], v[16:17]
	v_mov_b32_e32 v18, v1
	v_pk_fma_f32 v[6:7], v[6:7], v[6:7], v[16:17]
	v_mov_b32_e32 v16, v22
	v_mov_b32_e32 v17, v14
	v_mov_b32_e32 v19, v9
	v_pk_fma_f32 v[6:7], v[16:17], v[16:17], v[6:7]
	v_mov_b32_e32 v16, v0
	v_mov_b32_e32 v17, v8
	v_pk_mul_f32 v[18:19], v[18:19], v[18:19]
	v_mov_b32_e32 v4, v23
	v_mov_b32_e32 v5, v15
	v_pk_fma_f32 v[16:17], v[16:17], v[16:17], v[18:19]
	v_mov_b32_e32 v18, v2
	v_mov_b32_e32 v19, v10
	v_pk_fma_f32 v[4:5], v[4:5], v[4:5], v[6:7]
	v_mov_b32_e32 v6, v3
	v_mov_b32_e32 v7, v11
	v_pk_fma_f32 v[16:17], v[18:19], v[18:19], v[16:17]
	v_add_f32_e32 v4, v4, v5
	v_pk_fma_f32 v[6:7], v[6:7], v[6:7], v[16:17]
	v_mov_b32_e32 v16, v164
	v_mov_b32_e32 v17, v165
	v_mov_b32_e32 v18, v166
	v_mov_b32_e32 v19, v167
	v_add_f32_e32 v4, v7, v4
	v_add_f32_e32 v4, v6, v4
	ds_bpermute_b32 v5, v81, v4
	v_lshlrev_b64 v[6:7], 11, v[106:107]
	s_waitcnt lgkmcnt(0)
	v_add_f32_e32 v4, v4, v5
	ds_bpermute_b32 v5, v87, v4
	s_waitcnt lgkmcnt(0)
	v_add_f32_e32 v4, v4, v5
	s_nop 1
	v_mov_b32_dpp v5, v4 row_ror:8 row_mask:0xf bank_mask:0xf
	s_waitcnt lgkmcnt(0)
	v_add_f32_e32 v4, v4, v5
	s_nop 1
	v_mov_b32_dpp v5, v4 row_ror:4 row_mask:0xf bank_mask:0xf
	s_waitcnt lgkmcnt(0)
	v_add_f32_e32 v4, v4, v5
	s_nop 1
	v_mov_b32_dpp v5, v4 row_ror:2 row_mask:0xf bank_mask:0xf
	s_waitcnt lgkmcnt(0)
	v_add_f32_e32 v4, v4, v5
	s_nop 1
	v_mov_b32_dpp v5, v4 row_ror:1 row_mask:0xf bank_mask:0xf
	s_waitcnt lgkmcnt(0)
	v_add_f32_e32 v4, v4, v5
	v_fmamk_f32 v4, v4, 0x3a800000, v211
	v_cmp_gt_f32_e32 vcc, s94, v4
	v_mul_f32_e32 v5, 0x4b800000, v4
	s_nop 0
	v_cndmask_b32_e32 v4, v4, v5, vcc
	v_rsq_f32_e32 v4, v4
	s_nop 0
	v_mul_f32_e32 v5, 0x45800000, v4
	v_cndmask_b32_e32 v4, v4, v5, vcc
	v_pk_mul_f32 v[20:21], v[20:21], v[4:5] op_sel_hi:[1,0]
	v_pk_mul_f32 v[0:1], v[0:1], v[4:5] op_sel_hi:[1,0]
	v_pk_mul_f32 v[2:3], v[2:3], v[4:5] op_sel_hi:[1,0]
	s_nop 0
	v_pk_mul_f32 v[16:17], v[16:17], v[20:21]
	v_pk_mul_f32 v[20:21], v[22:23], v[4:5] op_sel_hi:[1,0]
	v_cvt_pk_bf16_f32 v16, v16, v17
	v_pk_mul_f32 v[18:19], v[18:19], v[20:21]
	v_lshl_add_u64 v[20:21], v[102:103], 0, v[6:7]
	v_cvt_pk_bf16_f32 v17, v18, v19
	global_store_dwordx2 v[20:21], v[16:17], off
	v_mov_b32_e32 v16, v168
	v_mov_b32_e32 v17, v169
	v_mov_b32_e32 v18, v170
	v_mov_b32_e32 v19, v171
	v_pk_mul_f32 v[6:7], v[12:13], v[4:5] op_sel_hi:[1,0]
	v_pk_mul_f32 v[12:13], v[14:15], v[4:5] op_sel_hi:[1,0]
	s_nop 0
	v_pk_mul_f32 v[6:7], v[16:17], v[6:7]
	v_pk_mul_f32 v[12:13], v[12:13], v[18:19]
	v_cvt_pk_bf16_f32 v6, v6, v7
	v_cvt_pk_bf16_f32 v7, v12, v13
	global_store_dwordx2 v[20:21], v[6:7], off offset:512
	v_mov_b32_e32 v12, v172
	v_mov_b32_e32 v13, v173
	v_mov_b32_e32 v14, v174
	v_mov_b32_e32 v15, v175
	v_pk_mul_f32 v[6:7], v[8:9], v[4:5] op_sel_hi:[1,0]
	v_pk_mul_f32 v[8:9], v[10:11], v[4:5] op_sel_hi:[1,0]
	s_nop 0
	v_pk_mul_f32 v[6:7], v[6:7], v[12:13]
	v_pk_mul_f32 v[8:9], v[8:9], v[14:15]
	v_cvt_pk_bf16_f32 v6, v6, v7
	v_cvt_pk_bf16_f32 v7, v8, v9
	global_store_dwordx2 v[20:21], v[6:7], off offset:1024
	v_mov_b32_e32 v6, v176
	v_mov_b32_e32 v7, v177
	v_mov_b32_e32 v8, v178
	v_mov_b32_e32 v9, v179
	s_nop 0
	v_pk_mul_f32 v[0:1], v[0:1], v[6:7]
	v_pk_mul_f32 v[2:3], v[2:3], v[8:9]
	v_cvt_pk_bf16_f32 v0, v0, v1
	v_cvt_pk_bf16_f32 v1, v2, v3
	global_store_dwordx2 v[20:21], v[0:1], off offset:1536
